# adds: GDN scan A-fragment LDS reads software-pipelined 10 deep into a rotating register pool with counted lgkmcnt waits (was ~30 serialized read-wait-MFMA round trips per chunk)
# speedup vs baseline: 1.0756x; 1.0033x over previous
.LBB0_824:
	s_waitcnt vmcnt(9)
	s_nop 0
	v_add_u32_e32 v58, 32, v122
	v_ashrrev_i32_e32 v123, 31, v122
	v_ashrrev_i32_e32 v59, 31, v58
	v_lshlrev_b64 v[126:127], 11, v[122:123]
	v_lshlrev_b64 v[124:125], 11, v[58:59]
	s_ashr_i32 s23, s22, 31
	v_lshl_add_u64 v[56:57], v[96:97], 0, v[126:127]
	v_lshl_add_u64 v[58:59], v[96:97], 0, v[124:125]
	v_lshl_add_u64 v[64:65], v[100:101], 0, s[0:1]
	s_lshl_b64 s[0:1], s[22:23], 2
	global_load_dwordx4 v[60:63], v[56:57], off nt
	s_nop 0
	global_load_dwordx4 v[56:59], v[58:59], off nt
	s_nop 0
	global_load_dwordx2 v[120:121], v[64:65], off offset:-64 nt
	global_load_dwordx2 v[118:119], v[64:65], off offset:-32 nt
	global_load_dwordx2 v[116:117], v[64:65], off nt
	global_load_dwordx2 v[114:115], v[64:65], off offset:32 nt
	s_add_u32 s0, s33, s0
	s_addc_u32 s1, s96, s1
	global_load_dword v104, v77, s[0:1]
	v_cndmask_b32_e64 v64, 0, 1, s[20:21]
	v_cmp_ne_u32_e64 s[0:1], 1, v64
	s_andn2_b64 vcc, exec, s[20:21]
	s_cbranch_vccnz .LBB0_826
	ds_read2_b64 v[168:171], v130 offset1:4
	v_add_u32_e32 v201, 0x800, v130
	ds_read2_b64 v[172:175], v201 offset0:32 offset1:36
	ds_read2_b64 v[176:179], v130 offset0:8 offset1:12
	ds_read2_b64 v[180:183], v201 offset0:40 offset1:44
	v_add_u32_e32 v202, 0x1000, v130
	ds_read2_b64 v[184:187], v202 offset0:64 offset1:68
	ds_read2_b64 v[188:191], v202 offset0:72 offset1:76
	v_add_u32_e32 v203, 0x1800, v130
	ds_read2_b64 v[192:195], v203 offset0:104 offset1:108
	ds_read2_b64 v[204:207], v203 offset0:96 offset1:100
	v_add_u32_e32 v201, 0x2000, v130
	ds_read2_b64 v[208:211], v201 offset0:128 offset1:132
	v_add_u32_e32 v202, 0x4800, v130
	ds_read2_b64 v[212:215], v202 offset1:4
	v_add_u32_e32 v75, 0x800, v130
	s_waitcnt vmcnt(15)
	v_lshlrev_b32_e32 v140, 16, v112
	v_and_b32_e32 v141, 0xffff0000, v112
	v_lshlrev_b32_e32 v142, 16, v113
	v_and_b32_e32 v143, 0xffff0000, v113
	v_cvt_pk_bf16_f32 v68, v24, v25
	v_cvt_pk_bf16_f32 v69, v26, v27
	v_cvt_pk_bf16_f32 v70, v28, v29
	v_cvt_pk_bf16_f32 v71, v30, v31
	v_add_u32_e32 v89, 0x1000, v130
	s_waitcnt lgkmcnt(9)
	v_mfma_f32_16x16x32_bf16 v[140:143], v[168:171], v[68:71], v[140:143]
	ds_read2_b64 v[216:219], v201 offset0:136 offset1:140
	s_waitcnt vmcnt(14)
	v_lshlrev_b32_e32 v72, 16, v110
	v_and_b32_e32 v73, 0xffff0000, v110
	v_lshlrev_b32_e32 v74, 16, v111
	v_and_b32_e32 v75, 0xffff0000, v111
	v_cvt_pk_bf16_f32 v64, v32, v33
	s_waitcnt lgkmcnt(9)
	v_mfma_f32_16x16x32_bf16 v[72:75], v[172:175], v[68:71], v[72:75]
	ds_read2_b64 v[220:223], v202 offset0:8 offset1:12
	v_cvt_pk_bf16_f32 v65, v34, v35
	v_cvt_pk_bf16_f32 v66, v36, v37
	v_cvt_pk_bf16_f32 v67, v38, v39
	s_waitcnt vmcnt(12)
	v_lshlrev_b32_e32 v152, 16, v106
	v_and_b32_e32 v153, 0xffff0000, v106
	s_waitcnt lgkmcnt(9)
	v_mfma_f32_16x16x32_bf16 v[140:143], v[176:179], v[64:67], v[140:143]
	v_add_u32_e32 v203, 0x2800, v130
	ds_read2_b64 v[224:227], v203 offset0:160 offset1:164
	v_lshlrev_b32_e32 v148, 16, v108
	v_and_b32_e32 v149, 0xffff0000, v108
	v_lshlrev_b32_e32 v150, 16, v109
	s_waitcnt lgkmcnt(9)
	v_mfma_f32_16x16x32_bf16 v[144:147], v[180:183], v[64:67], v[72:75]
	v_add_u32_e32 v201, 0x5000, v130
	ds_read2_b64 v[228:231], v201 offset0:32 offset1:36
	v_and_b32_e32 v151, 0xffff0000, v109
	v_lshlrev_b32_e32 v154, 16, v107
	v_and_b32_e32 v155, 0xffff0000, v107
	v_add_u32_e32 v89, 0x1800, v130
	s_waitcnt lgkmcnt(9)
	v_mfma_f32_16x16x32_bf16 v[108:111], v[184:187], v[68:71], v[148:151]
	ds_read2_b64 v[232:235], v203 offset0:168 offset1:172
	v_add_u32_e32 v106, 0x4800, v130
	v_add_u32_e32 v123, 0x5000, v130
	v_add_u32_e32 v89, 0x2000, v130
	s_waitcnt lgkmcnt(9)
	v_mfma_f32_16x16x32_bf16 v[108:111], v[188:191], v[64:67], v[108:111]
	ds_read2_b64 v[236:239], v201 offset0:40 offset1:44
	s_waitcnt vmcnt(11)
	v_pk_mul_f32 v[26:27], v[102:103], v[26:27] op_sel_hi:[0,1]
	v_pk_mul_f32 v[24:25], v[102:103], v[24:25] op_sel_hi:[0,1]
	v_pk_mul_f32 v[30:31], v[102:103], v[30:31] op_sel_hi:[0,1]
	s_waitcnt lgkmcnt(8)
	v_mfma_f32_16x16x32_bf16 v[72:75], v[204:207], v[68:71], v[152:155]
	v_add_u32_e32 v202, 0x3000, v130
	ds_read2_b64 v[240:243], v202 offset0:192 offset1:196
	s_nop 0
	v_cvt_pk_bf16_f32 v107, v110, v111
	v_pk_mul_f32 v[28:29], v[102:103], v[28:29] op_sel_hi:[0,1]
	s_waitcnt lgkmcnt(10)
	v_mfma_f32_16x16x32_bf16 v[152:155], v[192:195], v[64:67], v[72:75]
	v_add_u32_e32 v203, 0x5800, v130
	ds_read2_b64 v[244:247], v203 offset0:64 offset1:68
	v_pk_mul_f32 v[34:35], v[102:103], v[34:35] op_sel_hi:[0,1]
	v_pk_mul_f32 v[32:33], v[102:103], v[32:33] op_sel_hi:[0,1]
	v_cvt_pk_bf16_f32 v72, v140, v141
	v_cvt_pk_bf16_f32 v73, v142, v143
	s_waitcnt lgkmcnt(9)
	v_mfma_f32_16x16x32_bf16 v[140:143], v[208:211], v[68:71], 0
	ds_read2_b64 v[248:251], v202 offset0:200 offset1:204
	v_cvt_pk_bf16_f32 v74, v144, v145
	v_cvt_pk_bf16_f32 v75, v146, v147
	v_cvt_pk_bf16_f32 v106, v108, v109
	s_waitcnt lgkmcnt(9)
	v_mfma_f32_16x16x32_bf16 v[140:143], v[212:215], v[72:75], v[140:143]
	ds_read2_b64 v[168:171], v203 offset0:72 offset1:76
	v_cvt_pk_bf16_f32 v108, v152, v153
	v_cvt_pk_bf16_f32 v109, v154, v155
	v_pk_mul_f32 v[38:39], v[102:103], v[38:39] op_sel_hi:[0,1]
	s_waitcnt lgkmcnt(9)
	v_mfma_f32_16x16x32_bf16 v[140:143], v[216:219], v[64:67], v[140:143]
	v_add_u32_e32 v201, 0x3800, v130
	ds_read2_b64 v[172:175], v201 offset0:224 offset1:228
	v_mul_f32_e64 v36, v102, v36
	v_mul_f32_e64 v37, v102, v37
	s_waitcnt lgkmcnt(9)
	v_mfma_f32_16x16x32_bf16 v[110:113], v[220:223], v[106:109], v[140:143]
	v_add_u32_e32 v202, 0x6000, v130
	ds_read2_b64 v[176:179], v202 offset0:96 offset1:100
	s_nop 7
	v_cvt_pk_bf16_f32 v89, v110, s0
	ds_write_b16 v138, v89
	v_cvt_pk_bf16_f32 v89, v111, s0
	ds_write_b16 v138, v89 offset:144
	v_cvt_pk_bf16_f32 v89, v112, s0
	ds_write_b16 v138, v89 offset:288
	v_cvt_pk_bf16_f32 v89, v113, s0
	ds_write_b16 v138, v89 offset:432
	v_add_u32_e32 v89, 0x2800, v130
	s_waitcnt lgkmcnt(13)
	v_mfma_f32_16x16x32_bf16 v[110:113], v[224:227], v[68:71], 0
	ds_read2_b64 v[180:183], v201 offset0:232 offset1:236
	s_waitcnt lgkmcnt(13)
	v_mfma_f32_16x16x32_bf16 v[110:113], v[228:231], v[72:75], v[110:113]
	ds_read2_b64 v[184:187], v202 offset0:104 offset1:108
	s_waitcnt lgkmcnt(13)
	v_mfma_f32_16x16x32_bf16 v[110:113], v[232:235], v[64:67], v[110:113]
	v_add_u32_e32 v203, 0x6800, v130
	ds_read2_b64 v[188:191], v203 offset0:128 offset1:132
	v_add_u32_e32 v123, 0x5800, v130
	s_waitcnt lgkmcnt(13)
	v_mfma_f32_16x16x32_bf16 v[110:113], v[236:239], v[106:109], v[110:113]
	ds_read2_b64 v[192:195], v203 offset0:136 offset1:140
	s_nop 7
	v_cvt_pk_bf16_f32 v89, v110, s0
	ds_write_b16 v138, v89 offset:2304
	v_cvt_pk_bf16_f32 v89, v111, s0
	ds_write_b16 v138, v89 offset:2448
	v_cvt_pk_bf16_f32 v89, v112, s0
	ds_write_b16 v138, v89 offset:2592
	v_cvt_pk_bf16_f32 v89, v113, s0
	ds_write_b16 v138, v89 offset:2736
	v_add_u32_e32 v89, 0x3000, v130
	s_waitcnt lgkmcnt(15)
	v_mfma_f32_16x16x32_bf16 v[110:113], v[240:243], v[68:71], 0
	v_add_u32_e32 v201, 0x7000, v130
	ds_read2_b64 v[204:207], v201 offset0:160 offset1:164
	s_waitcnt lgkmcnt(15)
	v_mfma_f32_16x16x32_bf16 v[110:113], v[244:247], v[72:75], v[110:113]
	ds_read2_b64 v[208:211], v201 offset0:168 offset1:172
	s_waitcnt lgkmcnt(15)
	v_mfma_f32_16x16x32_bf16 v[110:113], v[248:251], v[64:67], v[110:113]
	v_add_u32_e32 v202, 0x7800, v130
	ds_read2_b64 v[212:215], v202 offset0:192 offset1:196
	v_add_u32_e32 v123, 0x6000, v130
	s_waitcnt lgkmcnt(15)
	v_mfma_f32_16x16x32_bf16 v[110:113], v[168:171], v[106:109], v[110:113]
	ds_read2_b64 v[216:219], v202 offset0:200 offset1:204
	s_nop 7
	v_cvt_pk_bf16_f32 v89, v110, s0
	ds_write_b16 v138, v89 offset:4608
	v_cvt_pk_bf16_f32 v89, v111, s0
	ds_write_b16 v138, v89 offset:4752
	v_cvt_pk_bf16_f32 v89, v112, s0
	ds_write_b16 v138, v89 offset:4896
	v_cvt_pk_bf16_f32 v89, v113, s0
	ds_write_b16 v138, v89 offset:5040
	v_add_u32_e32 v89, 0x3800, v130
	s_waitcnt lgkmcnt(15)
	v_mfma_f32_16x16x32_bf16 v[68:71], v[172:175], v[68:71], 0
	v_add_u32_e32 v203, 0x8000, v130
	ds_read2_b64 v[220:223], v203 offset0:224 offset1:228
	s_waitcnt lgkmcnt(15)
	v_mfma_f32_16x16x32_bf16 v[68:71], v[176:179], v[72:75], v[68:71]
	ds_read2_b64 v[224:227], v203 offset0:232 offset1:236
	s_waitcnt lgkmcnt(15)
	v_mfma_f32_16x16x32_bf16 v[64:67], v[180:183], v[64:67], v[68:71]
	s_nop 4
	s_waitcnt lgkmcnt(15)
	v_mfma_f32_16x16x32_bf16 v[64:67], v[184:187], v[106:109], v[64:67]
	v_add_u32_e32 v68, 0x6800, v130
	s_nop 6
	v_cvt_pk_bf16_f32 v64, v64, s0
	ds_write_b16 v138, v64 offset:6912
	v_cvt_pk_bf16_f32 v64, v65, s0
	ds_write_b16 v138, v64 offset:7056
	v_cvt_pk_bf16_f32 v64, v66, s0
	ds_write_b16 v138, v64 offset:7200
	v_cvt_pk_bf16_f32 v64, v67, s0
	ds_write_b16 v138, v64 offset:7344
	s_waitcnt lgkmcnt(15)
	v_mfma_f32_16x16x32_bf16 v[24:27], v[188:191], v[72:75], v[24:27]
	v_add_u32_e32 v68, 0x7000, v130
	s_waitcnt lgkmcnt(15)
	v_mfma_f32_16x16x32_bf16 v[24:27], v[192:195], v[106:109], v[24:27]
	s_waitcnt lgkmcnt(13)
	v_mfma_f32_16x16x32_bf16 v[28:31], v[204:207], v[72:75], v[28:31]
	v_add_u32_e32 v68, 0x7800, v130
	s_waitcnt lgkmcnt(12)
	v_mfma_f32_16x16x32_bf16 v[28:31], v[208:211], v[106:109], v[28:31]
	s_waitcnt lgkmcnt(11)
	v_mfma_f32_16x16x32_bf16 v[32:35], v[212:215], v[72:75], v[32:35]
	v_add_u32_e32 v68, 0x8000, v130
	s_waitcnt lgkmcnt(10)
	v_mfma_f32_16x16x32_bf16 v[32:35], v[216:219], v[106:109], v[32:35]
	s_waitcnt lgkmcnt(5)
	v_mfma_f32_16x16x32_bf16 v[36:39], v[220:223], v[72:75], v[36:39]
	s_waitcnt lgkmcnt(4)
	v_mfma_f32_16x16x32_bf16 v[36:39], v[224:227], v[106:109], v[36:39]

.LBB0_828:
	s_min_u32 s10, s50, 61
	s_add_i32 s10, s10, 2
	s_mul_i32 s23, s10, 0x50000
	s_add_u32 s52, s16, s23
	s_addc_u32 s53, s17, 0
	s_add_i32 s10, s10, s49
	s_waitcnt vmcnt(9)
	v_add_u32_e32 v56, 64, v122
	v_add_u32_e32 v58, 0x60, v122
	v_lshl_add_u64 v[64:65], s[52:53], 0, v[76:77]
	v_mov_b32_e32 v89, v77
	s_lshl_b32 s10, s10, 3
	v_ashrrev_i32_e32 v57, 31, v56
	v_ashrrev_i32_e32 v59, 31, v58
	v_lshl_add_u64 v[64:65], v[64:65], 0, v[88:89]
	s_or_b32 s52, s10, s46
	v_lshlrev_b64 v[56:57], 11, v[56:57]
	v_lshlrev_b64 v[58:59], 11, v[58:59]
	v_lshl_add_u64 v[66:67], v[64:65], 0, s[12:13]
	v_add_co_u32_e32 v64, vcc, s40, v64
	s_ashr_i32 s53, s52, 31
	v_lshl_add_u64 v[56:57], v[96:97], 0, v[56:57]
	v_lshl_add_u64 v[58:59], v[96:97], 0, v[58:59]
	v_addc_co_u32_e32 v65, vcc, 0, v65, vcc
	s_lshl_b64 s[52:53], s[52:53], 2
	global_load_dwordx4 v[60:63], v[56:57], off nt
	s_nop 0
	global_load_dwordx4 v[56:59], v[58:59], off nt
	s_nop 0
	global_load_dwordx2 v[112:113], v[64:65], off nt
	global_load_dwordx2 v[110:111], v[66:67], off offset:32 nt
	global_load_dwordx2 v[108:109], v[66:67], off offset:64 nt
	global_load_dwordx2 v[106:107], v[66:67], off offset:96 nt
	s_add_u32 s52, s33, s52
	s_addc_u32 s53, s96, s53
	global_load_dword v102, v77, s[52:53]
	s_and_b64 vcc, exec, s[0:1]
	s_cbranch_vccnz .LBB0_819
	v_add_u32_e32 v201, 0x9000, v130
	ds_read2_b64 v[168:171], v201 offset1:4
	v_add_u32_e32 v202, 0x9800, v130
	ds_read2_b64 v[172:175], v202 offset0:32 offset1:36
	ds_read2_b64 v[176:179], v201 offset0:8 offset1:12
	v_add_u32_e32 v203, 0xa000, v130
	ds_read2_b64 v[180:183], v203 offset0:64 offset1:68
	ds_read2_b64 v[184:187], v202 offset0:40 offset1:44
	ds_read2_b64 v[188:191], v203 offset0:72 offset1:76
	v_add_u32_e32 v201, 0xa800, v130
	ds_read2_b64 v[192:195], v201 offset0:96 offset1:100
	ds_read2_b64 v[204:207], v201 offset0:104 offset1:108
	v_add_u32_e32 v202, 0xb000, v130
	ds_read2_b64 v[208:211], v202 offset0:128 offset1:132
	v_add_u32_e32 v203, 0xd800, v130
	ds_read2_b64 v[212:215], v203 offset1:4
	v_add_u32_e32 v64, 0x9000, v130
	v_add_u32_e32 v75, 0x9800, v130
	s_waitcnt vmcnt(15)
	v_lshlrev_b32_e32 v122, 16, v120
	v_and_b32_e32 v123, 0xffff0000, v120
	v_lshlrev_b32_e32 v124, 16, v121
	v_and_b32_e32 v125, 0xffff0000, v121
	v_cvt_pk_bf16_f32 v68, v24, v25
	v_cvt_pk_bf16_f32 v69, v26, v27
	v_cvt_pk_bf16_f32 v70, v28, v29
	v_cvt_pk_bf16_f32 v71, v30, v31
	v_add_u32_e32 v89, 0xa000, v130
	s_waitcnt lgkmcnt(9)
	v_mfma_f32_16x16x32_bf16 v[120:123], v[168:171], v[68:71], v[122:125]
	ds_read2_b64 v[216:219], v202 offset0:136 offset1:140
	s_waitcnt vmcnt(14)
	v_lshlrev_b32_e32 v72, 16, v118
	v_and_b32_e32 v73, 0xffff0000, v118
	v_lshlrev_b32_e32 v74, 16, v119
	v_and_b32_e32 v75, 0xffff0000, v119
	v_cvt_pk_bf16_f32 v64, v32, v33
	v_cvt_pk_bf16_f32 v65, v34, v35
	s_waitcnt lgkmcnt(9)
	v_mfma_f32_16x16x32_bf16 v[72:75], v[172:175], v[68:71], v[72:75]
	ds_read2_b64 v[220:223], v203 offset0:8 offset1:12
	v_cvt_pk_bf16_f32 v66, v36, v37
	v_cvt_pk_bf16_f32 v67, v38, v39
	s_waitcnt vmcnt(11)
	v_pk_mul_f32 v[26:27], v[104:105], v[26:27] op_sel_hi:[0,1]
	v_pk_mul_f32 v[24:25], v[104:105], v[24:25] op_sel_hi:[0,1]
	s_waitcnt lgkmcnt(9)
	v_mfma_f32_16x16x32_bf16 v[120:123], v[176:179], v[64:67], v[120:123]
	v_add_u32_e32 v201, 0xb800, v130
	ds_read2_b64 v[224:227], v201 offset0:160 offset1:164
	v_lshlrev_b32_e32 v144, 16, v116
	v_and_b32_e32 v145, 0xffff0000, v116
	v_lshlrev_b32_e32 v146, 16, v117
	s_waitcnt lgkmcnt(8)
	v_mfma_f32_16x16x32_bf16 v[124:127], v[184:187], v[64:67], v[72:75]
	v_add_u32_e32 v202, 0xe000, v130
	ds_read2_b64 v[228:231], v202 offset0:32 offset1:36
	v_and_b32_e32 v147, 0xffff0000, v117
	v_pk_mul_f32 v[30:31], v[104:105], v[30:31] op_sel_hi:[0,1]
	v_pk_mul_f32 v[28:29], v[104:105], v[28:29] op_sel_hi:[0,1]
	v_add_u32_e32 v89, 0xa800, v130
	s_waitcnt lgkmcnt(10)
	v_mfma_f32_16x16x32_bf16 v[116:119], v[180:183], v[68:71], v[144:147]
	ds_read2_b64 v[232:235], v201 offset0:168 offset1:172
	v_add_u32_e32 v89, 0xb000, v130
	v_lshlrev_b32_e32 v144, 16, v114
	v_and_b32_e32 v145, 0xffff0000, v114
	v_lshlrev_b32_e32 v146, 16, v115
	v_and_b32_e32 v147, 0xffff0000, v115
	s_waitcnt lgkmcnt(9)
	v_mfma_f32_16x16x32_bf16 v[116:119], v[188:191], v[64:67], v[116:119]
	ds_read2_b64 v[236:239], v202 offset0:40 offset1:44
	v_add_u32_e32 v114, 0xd800, v130
	v_pk_mul_f32 v[34:35], v[104:105], v[34:35] op_sel_hi:[0,1]
	v_pk_mul_f32 v[32:33], v[104:105], v[32:33] op_sel_hi:[0,1]
	s_waitcnt lgkmcnt(9)
	v_mfma_f32_16x16x32_bf16 v[72:75], v[192:195], v[68:71], v[144:147]
	v_add_u32_e32 v203, 0xc000, v130
	ds_read2_b64 v[240:243], v203 offset0:192 offset1:196
	s_nop 1
	v_cvt_pk_bf16_f32 v115, v118, v119
	v_pk_mul_f32 v[38:39], v[104:105], v[38:39] op_sel_hi:[0,1]
	s_waitcnt lgkmcnt(9)
	v_mfma_f32_16x16x32_bf16 v[144:147], v[204:207], v[64:67], v[72:75]
	v_add_u32_e32 v201, 0xe800, v130
	ds_read2_b64 v[244:247], v201 offset0:64 offset1:68
	v_pk_mul_f32 v[36:37], v[104:105], v[36:37] op_sel_hi:[0,1]
	s_nop 0
	v_cvt_pk_bf16_f32 v72, v120, v121
	v_cvt_pk_bf16_f32 v73, v122, v123
	s_waitcnt lgkmcnt(9)
	v_mfma_f32_16x16x32_bf16 v[120:123], v[208:211], v[68:71], 0
	ds_read2_b64 v[248:251], v203 offset0:200 offset1:204
	v_cvt_pk_bf16_f32 v74, v124, v125
	v_cvt_pk_bf16_f32 v75, v126, v127
	v_cvt_pk_bf16_f32 v114, v116, v117
	s_waitcnt lgkmcnt(9)
	v_mfma_f32_16x16x32_bf16 v[120:123], v[212:215], v[72:75], v[120:123]
	ds_read2_b64 v[168:171], v201 offset0:72 offset1:76
	v_cvt_pk_bf16_f32 v116, v144, v145
	v_cvt_pk_bf16_f32 v117, v146, v147
	s_waitcnt lgkmcnt(9)
	v_mfma_f32_16x16x32_bf16 v[120:123], v[216:219], v[64:67], v[120:123]
	v_add_u32_e32 v202, 0xc800, v130
	ds_read2_b64 v[172:175], v202 offset0:224 offset1:228
	s_waitcnt lgkmcnt(9)
	v_mfma_f32_16x16x32_bf16 v[118:121], v[220:223], v[114:117], v[120:123]
	v_add_u32_e32 v203, 0xf000, v130
	ds_read2_b64 v[176:179], v203 offset0:96 offset1:100
	v_add_u32_e32 v126, 0xe000, v130
	s_nop 6
	v_cvt_pk_bf16_f32 v89, v118, s0
	ds_write_b16 v139, v89
	v_cvt_pk_bf16_f32 v89, v119, s0
	ds_write_b16 v139, v89 offset:144
	v_cvt_pk_bf16_f32 v89, v120, s0
	ds_write_b16 v139, v89 offset:288
	v_cvt_pk_bf16_f32 v89, v121, s0
	ds_write_b16 v139, v89 offset:432
	v_add_u32_e32 v89, 0xb800, v130
	s_waitcnt lgkmcnt(13)
	v_mfma_f32_16x16x32_bf16 v[118:121], v[224:227], v[68:71], 0
	ds_read2_b64 v[180:183], v202 offset0:232 offset1:236
	s_waitcnt lgkmcnt(13)
	v_mfma_f32_16x16x32_bf16 v[118:121], v[228:231], v[72:75], v[118:121]
	ds_read2_b64 v[184:187], v203 offset0:104 offset1:108
	s_waitcnt lgkmcnt(13)
	v_mfma_f32_16x16x32_bf16 v[118:121], v[232:235], v[64:67], v[118:121]
	v_add_u32_e32 v201, 0xf800, v130
	ds_read2_b64 v[188:191], v201 offset0:128 offset1:132
	v_add_u32_e32 v126, 0xe800, v130
	s_waitcnt lgkmcnt(13)
	v_mfma_f32_16x16x32_bf16 v[118:121], v[236:239], v[114:117], v[118:121]
	ds_read2_b64 v[192:195], v201 offset0:136 offset1:140
	s_nop 7
	v_cvt_pk_bf16_f32 v89, v118, s0
	ds_write_b16 v139, v89 offset:2304
	v_cvt_pk_bf16_f32 v89, v119, s0
	ds_write_b16 v139, v89 offset:2448
	v_cvt_pk_bf16_f32 v89, v120, s0
	ds_write_b16 v139, v89 offset:2592
	v_cvt_pk_bf16_f32 v89, v121, s0
	ds_write_b16 v139, v89 offset:2736
	v_add_u32_e32 v89, 0xc000, v130
	s_waitcnt lgkmcnt(15)
	v_mfma_f32_16x16x32_bf16 v[118:121], v[240:243], v[68:71], 0
	v_add_u32_e32 v202, 0x800, v135
	ds_read2_b64 v[204:207], v202 offset0:32 offset1:36
	s_waitcnt lgkmcnt(15)
	v_mfma_f32_16x16x32_bf16 v[118:121], v[244:247], v[72:75], v[118:121]
	ds_read2_b64 v[208:211], v202 offset0:40 offset1:44
	s_waitcnt lgkmcnt(15)
	v_mfma_f32_16x16x32_bf16 v[118:121], v[248:251], v[64:67], v[118:121]
	v_add_u32_e32 v203, 0x1000, v135
	ds_read2_b64 v[212:215], v203 offset0:64 offset1:68
	s_waitcnt lgkmcnt(15)
	v_mfma_f32_16x16x32_bf16 v[118:121], v[168:171], v[114:117], v[118:121]
	ds_read2_b64 v[216:219], v203 offset0:72 offset1:76
	v_add_u32_e32 v122, 0xf000, v130
	s_nop 6
	v_cvt_pk_bf16_f32 v89, v118, s0
	ds_write_b16 v139, v89 offset:4608
	v_cvt_pk_bf16_f32 v89, v119, s0
	ds_write_b16 v139, v89 offset:4752
	v_cvt_pk_bf16_f32 v89, v120, s0
	ds_write_b16 v139, v89 offset:4896
	v_cvt_pk_bf16_f32 v89, v121, s0
	ds_write_b16 v139, v89 offset:5040
	v_add_u32_e32 v89, 0xc800, v130
	s_waitcnt lgkmcnt(15)
	v_mfma_f32_16x16x32_bf16 v[68:71], v[172:175], v[68:71], 0
	v_add_u32_e32 v201, 0x1800, v135
	ds_read2_b64 v[220:223], v201 offset0:96 offset1:100
	s_waitcnt lgkmcnt(15)
	v_mfma_f32_16x16x32_bf16 v[68:71], v[176:179], v[72:75], v[68:71]
	ds_read2_b64 v[224:227], v201 offset0:104 offset1:108
	s_waitcnt lgkmcnt(15)
	v_mfma_f32_16x16x32_bf16 v[64:67], v[180:183], v[64:67], v[68:71]
	s_nop 4
	s_waitcnt lgkmcnt(15)
	v_mfma_f32_16x16x32_bf16 v[64:67], v[184:187], v[114:117], v[64:67]
	v_add_u32_e32 v68, 0xf800, v130
	s_nop 6
	v_cvt_pk_bf16_f32 v64, v64, s0
	ds_write_b16 v139, v64 offset:6912
	v_cvt_pk_bf16_f32 v64, v65, s0
	ds_write_b16 v139, v64 offset:7056
	v_cvt_pk_bf16_f32 v64, v66, s0
	ds_write_b16 v139, v64 offset:7200
	v_cvt_pk_bf16_f32 v64, v67, s0
	ds_write_b16 v139, v64 offset:7344
	s_waitcnt lgkmcnt(15)
	v_mfma_f32_16x16x32_bf16 v[24:27], v[188:191], v[72:75], v[24:27]
	v_add_u32_e32 v68, 0x800, v135
	s_waitcnt lgkmcnt(15)
	v_mfma_f32_16x16x32_bf16 v[24:27], v[192:195], v[114:117], v[24:27]
	s_waitcnt lgkmcnt(13)
	v_mfma_f32_16x16x32_bf16 v[28:31], v[204:207], v[72:75], v[28:31]
	v_add_u32_e32 v68, 0x1000, v135
	s_waitcnt lgkmcnt(12)
	v_mfma_f32_16x16x32_bf16 v[28:31], v[208:211], v[114:117], v[28:31]
	s_waitcnt lgkmcnt(11)
	v_mfma_f32_16x16x32_bf16 v[32:35], v[212:215], v[72:75], v[32:35]
	v_add_u32_e32 v68, 0x1800, v135
	s_waitcnt lgkmcnt(10)
	v_mfma_f32_16x16x32_bf16 v[32:35], v[216:219], v[114:117], v[32:35]
	s_waitcnt lgkmcnt(5)
	v_mfma_f32_16x16x32_bf16 v[36:39], v[220:223], v[72:75], v[36:39]
	s_waitcnt lgkmcnt(4)
	v_mfma_f32_16x16x32_bf16 v[36:39], v[224:227], v[114:117], v[36:39]
	s_branch .LBB0_819
